# sliding-window attention: blocks dealt by XCD-contiguous virtual CU id (the 16 q-blocks of a (b,h) sequence share one XCD L2) instead of blockIdx; plus QK read ring and diff-attention epilogue rewrite
# baseline (speedup 1.0000x reference)
.LBB0_966:
	s_and_b64 vcc, exec, s[4:5]
	s_cbranch_vccz .LBB0_1175
	v_readlane_b32 s4, v255, 0
	v_readlane_b32 s5, v255, 1
	v_readlane_b32 s13, v255, 2
	s_and_b32 s72, s97, 7
	s_lshl_b32 s72, s72, 5
	s_lshr_b32 s73, s97, 3
	s_add_i32 s72, s72, s73
	v_mbcnt_lo_u32_b32 v14, -1, 0
	v_mbcnt_hi_u32_b32 v14, -1, v14
	s_cmpk_gt_i32 s72, 0x5ff
	s_cbranch_scc1 .LBB0_1175
	s_load_dwordx2 s[0:1], s[4:5], 0xc0
	v_readlane_b32 s2, v255, 11
	v_lshlrev_b32_e32 v17, 3, v14
	v_and_b32_e32 v0, 0x78, v17
	v_add_u32_e32 v15, s2, v14
	s_waitcnt lgkmcnt(0)
	s_add_u32 s73, s0, 0x2a800000
	s_addc_u32 s74, s1, 0
	s_add_u32 s75, s0, 0x3c800000
	s_addc_u32 s76, s1, 0
	s_add_u32 s77, s0, 0x400000
	s_addc_u32 s78, s1, 0
	s_ashr_i32 s0, s72, 9
	s_lshl_b32 s6, s0, 1
	s_lshr_b32 s3, 16, s6
	s_and_b32 s1, s72, 15
	s_sub_i32 s2, 4, s6
	s_add_i32 s3, s3, -1
	s_lshr_b32 s2, s1, s2
	s_and_b32 s14, s3, s1
	s_lshl_b32 s1, s72, 5
	s_and_b32 s1, s1, 0x3000
	s_or_b32 s1, s2, s1
	s_add_i32 s2, s6, 8
	s_bfe_u32 s7, s72, 0x30004
	s_lshl_b64 s[2:3], s[14:15], s2
	s_add_u32 s2, s2, s1
	s_addc_u32 s3, s3, 0
	s_mul_i32 s4, s3, 0x4800
	s_mul_hi_u32 s5, s2, 0x4800
	s_add_i32 s5, s5, s4
	s_mul_i32 s4, s2, 0x4800
	s_add_u32 s8, s73, s4
	s_mul_i32 s4, s0, 0xc00
	s_addc_u32 s9, s74, s5
	s_ashr_i32 s5, s4, 31
	s_lshl_b64 s[4:5], s[4:5], 1
	s_add_u32 s8, s8, s4
	s_addc_u32 s9, s9, s5
	s_lshl_b32 s10, s7, 8
	s_add_u32 s8, s8, s10
	s_addc_u32 s9, s9, 0
	s_mulk_i32 s1, 0x4800
	s_add_u32 s1, s73, s1
	s_addc_u32 s11, s74, 0
	s_add_u32 s1, s1, s4
	s_addc_u32 s4, s11, s5
	s_add_u32 s11, s1, s10
	s_addc_u32 s12, s4, 0
	s_add_u32 s46, s11, 0x800
	s_addc_u32 s47, s12, 0
	s_add_u32 s48, s11, 0x1000
	s_addc_u32 s49, s12, 0
	s_ashr_i32 s1, s0, 31
	s_lshl_b64 s[4:5], s[0:1], 25
	s_add_u32 s20, s75, s4
	s_addc_u32 s21, s76, s5
	s_lshl_b64 s[4:5], s[2:3], 11
	s_add_u32 s4, s20, s4
	s_addc_u32 s5, s21, s5
	s_add_u32 s50, s4, s10
	s_addc_u32 s51, s5, 0
	s_lshl_b64 s[0:1], s[0:1], 19
	s_add_u32 s4, s77, s0
	s_addc_u32 s5, s78, s1
	s_lshl_b64 s[0:1], s[2:3], 5
	s_add_u32 s0, s4, s0
	s_addc_u32 s1, s5, s1
	s_lshl_b32 s2, s7, 2
	s_add_u32 s52, s0, s2
	s_addc_u32 s53, s1, 0
	s_lshl_b32 s82, s14, 8
	v_readfirstlane_b32 s0, v15
	s_lshl_b32 s79, 0x2400, s6
	s_lshl_b32 s80, 0x400, s6
	s_lshl_b32 s81, 8, s6
	s_lshr_b32 s83, 0x1000, s6
	s_ashr_i32 s4, s0, 1
	s_add_i32 s0, s82, 0xffffff80
	s_cmp_lg_u32 s14, 0
	s_cselect_b32 s0, s0, 0
	s_mul_hi_u32 s1, s0, s79
	s_mul_i32 s0, s0, s79
	s_lshl_b64 s[0:1], s[0:1], 1
	s_add_u32 s2, s11, s0
	v_ashrrev_i32_e32 v218, 4, v15
	s_addc_u32 s3, s12, s1
	s_add_u32 s0, s48, s0
	s_waitcnt vmcnt(0)
	v_mul_lo_u32 v2, s79, v218
	s_addc_u32 s1, s49, s1
	v_or_b32_e32 v2, v2, v0
	s_lshl_b32 s5, 0x48000, s6
	v_mov_b32_e32 v3, v1
	v_add_u32_e32 v4, s5, v2
	v_lshlrev_b64 v[18:19], 1, v[2:3]
	v_mov_b32_e32 v5, v1
	v_lshlrev_b64 v[20:21], 1, v[4:5]
	v_lshl_add_u64 v[2:3], s[2:3], 0, v[18:19]
	v_lshl_add_u64 v[4:5], s[2:3], 0, v[20:21]
	global_load_dwordx4 v[196:199], v[2:3], off offset:2048
	global_load_dwordx4 v[200:203], v[4:5], off offset:2048
	v_mov_b32_e32 v2, s4
	s_movk_i32 s2, 0xffe0
	v_bfi_b32 v2, s2, v2, v14
	v_mul_lo_u32 v2, v2, s79
	v_lshrrev_b32_e32 v3, 2, v14
	v_and_or_b32 v2, v3, 8, v2
	v_mov_b32_e32 v3, v1
	v_lshl_add_u64 v[2:3], v[2:3], 1, s[8:9]
	global_load_dwordx4 v[176:179], v[2:3], off
	global_load_dwordx4 v[172:175], v[2:3], off offset:32
	global_load_dwordx4 v[168:171], v[2:3], off offset:64
	global_load_dwordx4 v[164:167], v[2:3], off offset:96
	global_load_dwordx4 v[160:163], v[2:3], off offset:128
	global_load_dwordx4 v[10:13], v[2:3], off offset:160
	global_load_dwordx4 v[6:9], v[2:3], off offset:192
	s_nop 0
	global_load_dwordx4 v[2:5], v[2:3], off offset:224
	v_lshl_add_u64 v[18:19], s[0:1], 0, v[18:19]
	v_lshl_add_u64 v[20:21], s[0:1], 0, v[20:21]
	global_load_dwordx4 v[204:207], v[18:19], off
	global_load_dwordx4 v[208:211], v[20:21], off
	s_movk_i32 s0, 0x70
	v_lshlrev_b32_e32 v21, 1, v0
	v_lshlrev_b32_e32 v20, 8, v218
	s_waitcnt vmcnt(0)
	v_and_b32_e32 v22, 0xfffff0, v218
	v_lshlrev_b32_e32 v23, 1, v218
	v_bitop3_b32 v25, v21, v15, s0 bitop3:0x78
	v_and_or_b32 v22, v23, 8, v22
	v_add3_u32 v23, 0, v20, v25
	v_add_u32_e32 v25, 32, v218
	v_and_b32_e32 v26, 0xfffff0, v25
	v_lshlrev_b32_e32 v25, 1, v25
	v_and_or_b32 v25, v25, 8, v26
	v_bfe_u32 v17, v17, 5, 2
	v_lshrrev_b32_e32 v24, 1, v218
	v_lshrrev_b32_e32 v22, 1, v22
	s_waitcnt vmcnt(0)
	v_lshrrev_b32_e32 v25, 1, v25
	v_and_b32_e32 v19, 0x70, v15
	v_or_b32_e32 v22, v22, v17
	v_or_b32_e32 v17, v25, v17
	v_and_b32_e32 v18, 63, v14
	v_lshlrev_b32_e32 v22, 9, v22
	v_lshlrev_b32_e32 v17, 9, v17
	v_bitop3_b32 v19, v21, v20, v19 bitop3:0xde
	v_and_b32_e32 v219, 31, v14
	v_bfe_u32 v220, v14, 5, 1
	v_lshlrev_b32_e32 v20, 3, v18
	s_cmp_lg_u32 0, -1
	s_cselect_b32 s0, 0, 0
	v_lshlrev_b32_e32 v221, 2, v220
	v_sub_u32_e32 v222, v219, v221
	v_lshlrev_b32_e32 v224, 8, v219
	ds_write_b128 v23, v[196:199] offset:32768
	ds_write_b128 v23, v[200:203] offset:40960
	v_and_b32_e32 v23, 3, v218
	v_and_or_b32 v23, v24, 4, v23
	v_lshlrev_b32_e32 v23, 6, v23
	v_and_b32_e32 v24, 48, v21
	v_lshlrev_b32_e32 v21, 4, v14
	v_or3_b32 v22, v22, v23, v24
	v_or3_b32 v17, v17, v23, v24
	v_and_b32_e32 v23, 0xc0, v21
	v_lshlrev_b32_e32 v14, 1, v14
	v_and_or_b32 v23, v20, 24, v23
	v_and_b32_e32 v14, 32, v14
	v_and_b32_e32 v20, 0x100, v20
	v_or3_b32 v14, v23, v14, v20
	v_add_u32_e32 v223, s0, v14
	v_lshlrev_b32_e32 v14, 4, v220
	v_and_b32_e32 v20, 0x70, v21
	v_or_b32_e32 v21, 32, v14
	v_xad_u32 v225, v14, v20, 0
	v_xad_u32 v226, v21, v20, 0
	v_or_b32_e32 v21, 64, v14
	v_or_b32_e32 v14, 0x60, v14
	v_xad_u32 v227, v21, v20, 0
	v_xad_u32 v228, v14, v20, 0
	v_cmp_gt_u32_e64 s[6:7], 32, v18
	v_lshlrev_b32_e32 v14, 3, v220
	v_add_u32_e32 v229, 0xffffff80, v222
	v_add_u32_e32 v230, 0, v22
	v_add_u32_e32 v231, 0, v17
	v_add_u32_e32 v232, 0, v19
	s_mov_b32 s3, s79
	s_waitcnt lgkmcnt(0)
	s_barrier
	s_branch .LBB0_970
